# attention unit prologue: q-norm weight loads issued in one batch; K/V ring DMA sets issued behind the q loads (latency under the q math)
# baseline (speedup 1.0000x reference)
; template <bool SHIFT> __device__ __forceinline__ void attn_dense_body(const bf16* __restrict__ Qb, const bf16* __restrict__ Kh, const bf16* __restrict__ Vh, bf16* __restrict__ Ob, int seq, char* lds, LAS unsigned char* ldsl, float negB, const float* __restrict__ gq, int qpos0) {
;     ...
;   const bf16* Qw = Qb + (long)(wid * QBLK + r32) * LDQ + hi * 8;
;   asm volatile("" : "+s"(gq));
;   { float ss = 0.f;
; #pragma unroll
;     for (int d0 = 0; d0 < 6; ++d0) { qr[d0] = *reinterpret_cast<const bf16x8*>(Qw + d0 * 16);
; #pragma unroll
;       for (int e = 0; e < 8; ++e) { const float f = __uint_as_float(((unsigned)(unsigned short)qr[d0][e]) << 16); ss += f * f; } }
;     { auto rr = __builtin_amdgcn_permlane32_swap(__float_as_uint(ss), __float_as_uint(ss), false, false); ss = __uint_as_float(rr[0]) + __uint_as_float(rr[1]); }
;     const float rstd = rsqrtf(ss * (1.0f / 96.0f) + EPS) * (SCALE * 1.4426950408889634f);
;     int lpos = qpos0 + wid * QBLK + r32; asm volatile("" : "+v"(lpos));
;     const float invf[8] = {1.0f, 0.31622776601683794f, 0.1f, 0.031622776601683794f, 0.01f, 0.0031622776601683794f, 0.001f, 0.00031622776601683794f};
; #pragma unroll
;     for (int d0 = 0; d0 < 6; ++d0) { float f[8];
;       const f32x4 g0 = *reinterpret_cast<const f32x4*>(gq + d0 * 16 + hi * 8), g1 = *reinterpret_cast<const f32x4*>(gq + d0 * 16 + hi * 8 + 4);
; #pragma unroll
;       for (int e = 0; e < 8; ++e) f[e] = __uint_as_float(((unsigned)(unsigned short)qr[d0][e]) << 16) * rstd * (e < 4 ? g0[e & 3] : g1[e & 3]);
;     ...
;   f32x16 pA0, pA1, pB0, pB1; bf16x8 pa0, pa1, pa2, pa3; const int NT = seq / KVBLK;
;   DMA(0, 0); asm volatile("s_waitcnt vmcnt(0)" ::: "memory"); __syncthreads();
;   DMA(1, KVBLK);
.LBB0_1591:
	s_lshl_b32 s4, s3, 4
	s_lshl_b32 s5, s3, 8
	s_and_b32 s4, s4, 0xfffff000
	s_and_b32 s58, s5, 0xf00
	s_ashr_i32 s33, s3, 4
	s_or_b32 s4, s4, s58
	s_and_b32 s38, s33, 15
	s_ashr_i32 s5, s4, 31
	s_mul_i32 s50, s4, 0xc00
	s_mul_hi_i32 s39, s4, 0xc00
	s_add_u32 s50, s12, s50
	s_addc_u32 s39, s13, s39
	s_mul_i32 s51, s38, 0xc0
	s_add_u32 s56, s50, s51
	s_addc_u32 s57, s39, 0
	s_lshl_b64 s[4:5], s[4:5], 11
	s_add_u32 s4, s42, s4
	s_mul_hi_i32 s51, s33, 0x110000
	s_mul_i32 s50, s33, 0x110000
	s_mul_hi_i32 s53, s33, 0x88000
	s_mul_i32 s52, s33, 0x88000
	s_addc_u32 s5, s43, s5
	s_lshl_b32 s33, s38, 7
	v_mov_b32_e32 v131, v81
	s_add_u32 s38, s4, s33
	v_lshl_add_u64 v[0:1], s[56:57], 0, v[130:131]
	v_mov_b32_e32 v133, v81
	s_addc_u32 s39, s5, 0
	v_lshl_add_u64 v[106:107], v[0:1], 0, v[132:133]
	s_mov_b64 s[4:5], -1
	s_and_b64 vcc, exec, s[8:9]
	v_add_u32_e32 v131, s58, v111
	v_lshlrev_b32_e32 v80, 2, v110
	s_cbranch_vccz .LBB0_1599
	s_mov_b64 s[4:5], s[0:1]
	s_load_dwordx2 s[4:5], s[4:5], 0xd0
	s_waitcnt lgkmcnt(0)
	global_load_dwordx4 v[0:3], v[106:107], off
	global_load_dwordx4 v[8:11], v[106:107], off offset:32
	global_load_dwordx4 v[12:15], v[106:107], off offset:64
	global_load_dwordx4 v[16:19], v[106:107], off offset:96
	global_load_dwordx4 v[20:23], v[106:107], off offset:128
	global_load_dwordx4 v[24:27], v[106:107], off offset:160
	v_mov_b32_e32 v44, v131
	v_lshl_add_u64 v[6:7], s[4:5], 0, v[80:81]
	flat_load_dwordx4 v[28:31], v[6:7]
	flat_load_dwordx4 v[32:35], v[6:7] offset:16
	flat_load_dwordx4 v[190:193], v[6:7] offset:64
	flat_load_dwordx4 v[194:197], v[6:7] offset:80
	flat_load_dwordx4 v[198:201], v[6:7] offset:128
	flat_load_dwordx4 v[202:205], v[6:7] offset:144
	flat_load_dwordx4 v[206:209], v[6:7] offset:192
	flat_load_dwordx4 v[210:213], v[6:7] offset:208
	flat_load_dwordx4 v[214:217], v[6:7] offset:256
	flat_load_dwordx4 v[218:221], v[6:7] offset:272
	flat_load_dwordx4 v[222:225], v[6:7] offset:320
	flat_load_dwordx4 v[226:229], v[6:7] offset:336
	s_waitcnt vmcnt(0)
	v_readfirstlane_b32 s60, v109
	s_add_u32 s56, s10, s50
	s_addc_u32 s57, s11, s51
	s_lshl_b32 s60, s60, 11
	s_add_u32 s56, s56, 0x12c00000
	s_addc_u32 s57, s57, 0
	s_add_u32 s58, s10, s52
	s_addc_u32 s59, s11, s53
	s_add_u32 s58, s58, 0x1bc00000
	s_addc_u32 s59, s59, 0
	s_add_i32 m0, s60, 0x0
	s_nop 0
	global_load_lds_dwordx4 v124, s[56:57]
	global_load_lds_dwordx4 v126, s[56:57] offset:1024
	s_add_u32 s56, s56, 0x4000
	s_addc_u32 s57, s57, 0
	s_add_i32 m0, s60, 0x4000
	s_nop 0
	global_load_lds_dwordx4 v124, s[56:57]
	global_load_lds_dwordx4 v126, s[56:57] offset:1024
	s_add_u32 s56, s56, 0x4000
	s_addc_u32 s57, s57, 0
	s_add_i32 m0, s60, 0xc000
	s_nop 0
	global_load_lds_dwordx4 v128, s[58:59]
	s_add_u32 s58, s58, 0x2000
	s_addc_u32 s59, s59, 0
	s_add_i32 m0, s60, 0x8000
	s_nop 0
	global_load_lds_dwordx4 v124, s[56:57]
	global_load_lds_dwordx4 v126, s[56:57] offset:1024
	s_add_u32 s56, s56, 0x4000
	s_addc_u32 s57, s57, 0
	s_add_i32 m0, s60, 0x10000
	s_nop 0
	global_load_lds_dwordx4 v128, s[58:59]
	s_add_u32 s58, s58, 0x2000
	s_addc_u32 s59, s59, 0
	v_and_b32_e32 v37, 0xffff0000, v0
	v_lshlrev_b32_e32 v36, 16, v0
	v_lshlrev_b32_e32 v38, 16, v1
	v_lshlrev_b32_e32 v61, 16, v16
	v_and_b32_e32 v62, 0xffff0000, v16
	v_mul_f32_e32 v16, v37, v37
	v_fmac_f32_e32 v16, v36, v36
	v_and_b32_e32 v39, 0xffff0000, v1
	v_fmac_f32_e32 v16, v38, v38
	v_lshlrev_b32_e32 v40, 16, v2
	v_fmac_f32_e32 v16, v39, v39
	v_and_b32_e32 v41, 0xffff0000, v2
	v_fmac_f32_e32 v16, v40, v40
	v_lshlrev_b32_e32 v42, 16, v3
	v_fmac_f32_e32 v16, v41, v41
	v_and_b32_e32 v43, 0xffff0000, v3
	v_fmac_f32_e32 v16, v42, v42
	v_lshlrev_b32_e32 v45, 16, v8
	v_fmac_f32_e32 v16, v43, v43
	v_and_b32_e32 v46, 0xffff0000, v8
	v_fmac_f32_e32 v16, v45, v45
	v_lshlrev_b32_e32 v47, 16, v9
	v_fmac_f32_e32 v16, v46, v46
	v_and_b32_e32 v48, 0xffff0000, v9
	v_fmac_f32_e32 v16, v47, v47
	v_lshlrev_b32_e32 v49, 16, v10
	v_fmac_f32_e32 v16, v48, v48
	v_and_b32_e32 v50, 0xffff0000, v10
	v_fmac_f32_e32 v16, v49, v49
	v_lshlrev_b32_e32 v51, 16, v11
	v_fmac_f32_e32 v16, v50, v50
	v_and_b32_e32 v52, 0xffff0000, v11
	v_fmac_f32_e32 v16, v51, v51
	v_lshlrev_b32_e32 v53, 16, v12
	v_fmac_f32_e32 v16, v52, v52
	v_and_b32_e32 v54, 0xffff0000, v12
	v_fmac_f32_e32 v16, v53, v53
	v_lshlrev_b32_e32 v55, 16, v13
	v_fmac_f32_e32 v16, v54, v54
	v_and_b32_e32 v56, 0xffff0000, v13
	v_fmac_f32_e32 v16, v55, v55
	v_lshlrev_b32_e32 v57, 16, v14
	v_fmac_f32_e32 v16, v56, v56
	v_and_b32_e32 v58, 0xffff0000, v14
	v_fmac_f32_e32 v16, v57, v57
	v_lshlrev_b32_e32 v59, 16, v15
	v_fmac_f32_e32 v16, v58, v58
	v_and_b32_e32 v60, 0xffff0000, v15
	v_fmac_f32_e32 v16, v59, v59
	v_fmac_f32_e32 v16, v60, v60
	v_fmac_f32_e32 v16, v61, v61
	v_lshlrev_b32_e32 v63, 16, v17
	v_fmac_f32_e32 v16, v62, v62
	v_and_b32_e32 v64, 0xffff0000, v17
	v_fmac_f32_e32 v16, v63, v63
	v_lshlrev_b32_e32 v65, 16, v18
	v_fmac_f32_e32 v16, v64, v64
	v_and_b32_e32 v66, 0xffff0000, v18
	v_fmac_f32_e32 v16, v65, v65
	v_lshlrev_b32_e32 v67, 16, v19
	v_fmac_f32_e32 v16, v66, v66
	v_and_b32_e32 v68, 0xffff0000, v19
	v_fmac_f32_e32 v16, v67, v67
	v_lshlrev_b32_e32 v69, 16, v20
	v_fmac_f32_e32 v16, v68, v68
	v_and_b32_e32 v70, 0xffff0000, v20
	v_fmac_f32_e32 v16, v69, v69
	v_lshlrev_b32_e32 v71, 16, v21
	v_fmac_f32_e32 v16, v70, v70
	v_and_b32_e32 v72, 0xffff0000, v21
	v_fmac_f32_e32 v16, v71, v71
	v_lshlrev_b32_e32 v73, 16, v22
	v_fmac_f32_e32 v16, v72, v72
	v_and_b32_e32 v74, 0xffff0000, v22
	v_fmac_f32_e32 v16, v73, v73
	v_lshlrev_b32_e32 v75, 16, v23
	v_fmac_f32_e32 v16, v74, v74
	v_and_b32_e32 v76, 0xffff0000, v23
	v_fmac_f32_e32 v16, v75, v75
	v_lshlrev_b32_e32 v8, 16, v24
	v_fmac_f32_e32 v16, v76, v76
	v_and_b32_e32 v9, 0xffff0000, v24
	v_and_b32_e32 v5, 0xffff0000, v25
	v_lshlrev_b32_e32 v4, 16, v25
	v_fmac_f32_e32 v16, v8, v8
	v_pk_mul_f32 v[10:11], v[4:5], v[4:5]
	v_fmac_f32_e32 v16, v9, v9
	v_and_b32_e32 v3, 0xffff0000, v26
	v_lshlrev_b32_e32 v2, 16, v26
	v_add_f32_e32 v10, v10, v16
	v_pk_mul_f32 v[12:13], v[2:3], v[2:3]
	v_add_f32_e32 v10, v11, v10
	v_and_b32_e32 v1, 0xffff0000, v27
	v_lshlrev_b32_e32 v0, 16, v27
	v_add_f32_e32 v10, v12, v10
	v_pk_mul_f32 v[14:15], v[0:1], v[0:1]
	v_add_f32_e32 v10, v13, v10
	v_add_f32_e32 v10, v14, v10
	v_add_f32_e32 v10, v15, v10
	v_mov_b32_e32 v11, v10
	s_nop 1
	v_permlane32_swap_b32_e32 v10, v11
	v_add_f32_e32 v10, v10, v11
	v_fmamk_f32 v10, v10, 0x3c2aaaab, v155
	v_mul_f32_e32 v11, 0x4b800000, v10
	v_cmp_gt_f32_e32 vcc, s44, v10
	s_nop 1
	v_cndmask_b32_e32 v10, v10, v11, vcc
	v_rsq_f32_e32 v10, v10
	s_nop 0
	v_mul_f32_e32 v11, 0x45800000, v10
	v_cndmask_b32_e32 v10, v10, v11, vcc
	v_mul_f32_e32 v10, 0x3e16c740, v10
	v_mul_f32_e32 v11, v10, v36
	v_mul_f32_e32 v12, v10, v37
	v_mul_f32_e32 v13, v10, v38
	v_mul_f32_e32 v14, v10, v39
	v_mul_f32_e32 v15, v10, v40
	v_mul_f32_e32 v16, v10, v41
	v_mul_f32_e32 v17, v10, v42
	v_mul_f32_e32 v18, v10, v43
	s_waitcnt lgkmcnt(0)
; __device__ __forceinline__ u32x4 pack8f(const float* f) { u32x4 w; w.x = cvt_pk_bf16(f[0], f[1]); w.y = cvt_pk_bf16(f[2], f[3]); w.z = cvt_pk_bf16(f[4], f[5]); w.w = cvt_pk_bf16(f[6], f[7]); return w; }
; template <bool SHIFT> __device__ __forceinline__ void attn_dense_body(const bf16* __restrict__ Qb, const bf16* __restrict__ Kh, const bf16* __restrict__ Vh, bf16* __restrict__ Ob, int seq, char* lds, LAS unsigned char* ldsl, float negB, const float* __restrict__ gq, int qpos0) {
;     ...
; #pragma unroll
;     for (int d0 = 0; d0 < 6; ++d0) { float f[8];
;       const f32x4 g0 = *reinterpret_cast<const f32x4*>(gq + d0 * 16 + hi * 8), g1 = *reinterpret_cast<const f32x4*>(gq + d0 * 16 + hi * 8 + 4);
; #pragma unroll
;       for (int e = 0; e < 8; ++e) f[e] = __uint_as_float(((unsigned)(unsigned short)qr[d0][e]) << 16) * rstd * (e < 4 ? g0[e & 3] : g1[e & 3]);
;       if (d0 >= 4) { const float pos = (d0 == 5) ? (float)(lpos & 63) : (float)(lpos >> 6);
; #pragma unroll
;         for (int e = 0; e < 8; ++e) { const float own = f[e];
;           auto rr = __builtin_amdgcn_permlane32_swap(__float_as_uint(own), __float_as_uint(own), false, false);
;           const float other = hi ? __uint_as_float(rr[0]) : __uint_as_float(rr[1]);
;           const float ang = pos * invf[e], cs = __cosf(ang), sn = __sinf(ang);
;           f[e] = own * cs + (hi ? other : -other) * sn; } }
;       u32x4 w = pack8f(f); qr[d0] = *reinterpret_cast<bf16x8*>(&w);
;       asm volatile("" : "+v"(qr[d0])); }
	v_mul_f32_e32 v11, v28, v11
	v_mul_f32_e32 v12, v29, v12
	v_mul_f32_e32 v13, v30, v13
	v_mul_f32_e32 v14, v31, v14
	v_mul_f32_e32 v15, v32, v15
	v_mul_f32_e32 v16, v33, v16
	v_mul_f32_e32 v17, v34, v17
	v_mul_f32_e32 v18, v35, v18
	v_cvt_pk_bf16_f32 v86, v11, v12
	v_cvt_pk_bf16_f32 v87, v13, v14
	v_cvt_pk_bf16_f32 v88, v15, v16
	v_cvt_pk_bf16_f32 v89, v17, v18
	v_mul_f32_e32 v11, v10, v45
	v_mul_f32_e32 v20, v10, v46
	v_mul_f32_e32 v21, v10, v47
	v_mul_f32_e32 v22, v10, v48
	v_mul_f32_e32 v23, v10, v49
	v_mul_f32_e32 v24, v10, v50
	v_mul_f32_e32 v25, v10, v51
	v_mul_f32_e32 v26, v10, v52
	v_mul_f32_e32 v36, v10, v70
	v_mul_f32_e32 v37, v10, v71
	v_mul_f32_e32 v38, v10, v72
	v_mul_f32_e32 v39, v10, v73
	v_mul_f32_e32 v40, v10, v74
	v_mul_f32_e32 v41, v10, v75
	v_mul_f32_e32 v42, v10, v76
	v_mul_f32_e32 v8, v10, v8
	v_mul_f32_e32 v9, v10, v9
	v_mul_f32_e32 v4, v10, v4
	v_mul_f32_e32 v5, v10, v5
	v_mul_f32_e32 v3, v10, v3
	v_mul_f32_e32 v1, v10, v1
	v_mul_f32_e32 v11, v190, v11
	v_mul_f32_e32 v12, v191, v20
	v_mul_f32_e32 v13, v192, v21
	v_mul_f32_e32 v14, v193, v22
	v_mul_f32_e32 v15, v194, v23
	v_mul_f32_e32 v16, v195, v24
	v_mul_f32_e32 v17, v196, v25
	v_mul_f32_e32 v18, v197, v26
	v_cvt_pk_bf16_f32 v82, v11, v12
	v_cvt_pk_bf16_f32 v83, v13, v14
	v_cvt_pk_bf16_f32 v84, v15, v16
	v_cvt_pk_bf16_f32 v85, v17, v18
	v_mul_f32_e32 v11, v10, v53
	v_mul_f32_e32 v20, v10, v54
	v_mul_f32_e32 v21, v10, v55
	v_mul_f32_e32 v22, v10, v56
	v_mul_f32_e32 v23, v10, v57
	v_mul_f32_e32 v24, v10, v58
	v_mul_f32_e32 v25, v10, v59
	v_mul_f32_e32 v26, v10, v60
	v_mul_f32_e32 v11, v11, v198
	v_mul_f32_e32 v12, v20, v199
	v_mul_f32_e32 v13, v21, v200
	v_mul_f32_e32 v14, v22, v201
	v_mul_f32_e32 v15, v23, v202
	v_mul_f32_e32 v16, v24, v203
	v_mul_f32_e32 v17, v25, v204
	v_mul_f32_e32 v18, v26, v205
	v_cvt_pk_bf16_f32 v90, v11, v12
	v_cvt_pk_bf16_f32 v91, v13, v14
	v_cvt_pk_bf16_f32 v92, v15, v16
	v_cvt_pk_bf16_f32 v93, v17, v18
	v_mul_f32_e32 v11, v10, v61
	v_mul_f32_e32 v20, v10, v62
	v_mul_f32_e32 v21, v10, v63
	v_mul_f32_e32 v22, v10, v64
	v_mul_f32_e32 v23, v10, v65
	v_mul_f32_e32 v24, v10, v66
	v_mul_f32_e32 v25, v10, v67
	v_mul_f32_e32 v26, v10, v68
	v_mul_f32_e32 v11, v11, v206
	v_mul_f32_e32 v12, v20, v207
	v_mul_f32_e32 v13, v21, v208
	v_mul_f32_e32 v14, v22, v209
	v_mul_f32_e32 v15, v23, v210
	v_mul_f32_e32 v16, v24, v211
	v_mul_f32_e32 v17, v25, v212
	v_mul_f32_e32 v18, v26, v213
	v_cvt_pk_bf16_f32 v94, v11, v12
	v_cvt_pk_bf16_f32 v95, v13, v14
	v_cvt_pk_bf16_f32 v96, v15, v16
	v_cvt_pk_bf16_f32 v97, v17, v18
	v_ashrrev_i32_e32 v11, 6, v44
	v_cvt_f32_i32_e32 v11, v11
	v_mul_f32_e32 v20, 0x39a5cb5f, v11
	v_mul_f32_e32 v21, 0x3a83126f, v11
	v_mul_f32_e32 v22, 0x3b4f3e37, v11
	v_mul_f32_e32 v23, 0x3c23d70a, v11
	v_mul_f32_e32 v24, 0x3d0186e2, v11
	v_mul_f32_e32 v25, 0x3dcccccd, v11
	v_mul_f32_e32 v26, 0x3ea1e89b, v11
	v_mul_f32_e32 v11, 0.15915494, v11
	v_mul_f32_e32 v27, 0.15915494, v20
	v_mul_f32_e32 v28, 0.15915494, v21
	v_cos_f32_e32 v20, v11
	v_sin_f32_e32 v21, v11
	v_mul_f32_e32 v11, v10, v69
	v_mul_f32_e32 v29, 0.15915494, v22
	v_mul_f32_e32 v30, 0.15915494, v23
	v_mul_f32_e32 v31, 0.15915494, v24
	v_mul_f32_e32 v33, 0.15915494, v25
	v_mul_f32_e32 v35, 0.15915494, v26
	v_cos_f32_e32 v22, v27
	v_sin_f32_e32 v23, v27
	v_cos_f32_e32 v24, v28
	v_sin_f32_e32 v25, v28
	v_cos_f32_e32 v26, v29
	v_sin_f32_e32 v27, v29
	v_cos_f32_e32 v28, v30
	v_sin_f32_e32 v29, v30
	v_cos_f32_e32 v30, v31
	v_sin_f32_e32 v31, v31
	v_cos_f32_e32 v32, v33
	v_sin_f32_e32 v33, v33
	v_cos_f32_e32 v34, v35
	v_sin_f32_e32 v35, v35
	v_mul_f32_e32 v12, v11, v214
	v_mul_f32_e32 v36, v36, v215
	v_mul_f32_e32 v14, v37, v216
	v_mul_f32_e32 v38, v38, v217
	v_mul_f32_e32 v16, v39, v218
	v_mul_f32_e32 v40, v40, v219
	v_mul_f32_e32 v18, v41, v220
	v_mul_f32_e32 v42, v42, v221
	v_mov_b32_e32 v11, v12
	v_mov_b32_e32 v13, v12
	v_mov_b32_e32 v15, v36
	v_mov_b32_e32 v17, v36
	v_mov_b32_e32 v19, v14
	v_mov_b32_e32 v37, v14
	v_mov_b32_e32 v39, v38
	v_mov_b32_e32 v41, v38
	v_mov_b32_e32 v43, v16
	v_mov_b32_e32 v45, v16
	v_mov_b32_e32 v46, v40
	v_mov_b32_e32 v47, v40
	v_mov_b32_e32 v48, v18
	v_mov_b32_e32 v49, v18
	v_mov_b32_e32 v50, v42
	v_mov_b32_e32 v51, v42
	v_permlane32_swap_b32_e32 v11, v13
	v_permlane32_swap_b32_e32 v15, v17
	v_permlane32_swap_b32_e32 v19, v37
	v_permlane32_swap_b32_e32 v39, v41
	v_permlane32_swap_b32_e32 v43, v45
	v_permlane32_swap_b32_e32 v46, v47
	v_permlane32_swap_b32_e32 v48, v49
	v_permlane32_swap_b32_e32 v50, v51
	v_cndmask_b32_e64 v50, v50, v51, s[6:7]
	v_cndmask_b32_e64 v48, v48, v49, s[6:7]
	v_cndmask_b32_e64 v46, v46, v47, s[6:7]
	v_cndmask_b32_e64 v45, v43, v45, s[6:7]
	v_cndmask_b32_e64 v39, v39, v41, s[6:7]
	v_cndmask_b32_e64 v37, v19, v37, s[6:7]
	v_cndmask_b32_e64 v47, v15, v17, s[6:7]
	v_cndmask_b32_e64 v11, v11, v13, s[6:7]
	v_cndmask_b32_e64 v43, v50, -v50, s[6:7]
	v_cndmask_b32_e64 v19, v48, -v48, s[6:7]
	v_cndmask_b32_e64 v41, v46, -v46, s[6:7]
; #define LAS __attribute__((address_space(3)))
; __device__ __forceinline__ u32x4 pack8f(const float* f) { u32x4 w; w.x = cvt_pk_bf16(f[0], f[1]); w.y = cvt_pk_bf16(f[2], f[3]); w.z = cvt_pk_bf16(f[4], f[5]); w.w = cvt_pk_bf16(f[6], f[7]); return w; }
; __device__ __forceinline__ unsigned cvtpk(float lo, float hi) { unsigned r; asm volatile("v_cvt_pk_bf16_f32 %0, %1, %2" : "=v"(r) : "v"(lo), "v"(hi)); return r; }
; template <bool SHIFT> __device__ __forceinline__ void attn_dense_body(const bf16* __restrict__ Qb, const bf16* __restrict__ Kh, const bf16* __restrict__ Vh, bf16* __restrict__ Ob, int seq, char* lds, LAS unsigned char* ldsl, float negB, const float* __restrict__ gq, int qpos0) {
;     ...
;       if (d0 >= 4) { const float pos = (d0 == 5) ? (float)(lpos & 63) : (float)(lpos >> 6);
; #pragma unroll
;         for (int e = 0; e < 8; ++e) { const float own = f[e];
;           auto rr = __builtin_amdgcn_permlane32_swap(__float_as_uint(own), __float_as_uint(own), false, false);
;           const float other = hi ? __uint_as_float(rr[0]) : __uint_as_float(rr[1]);
;           const float ang = pos * invf[e], cs = __cosf(ang), sn = __sinf(ang);
;           f[e] = own * cs + (hi ? other : -other) * sn; } }
;       u32x4 w = pack8f(f); qr[d0] = *reinterpret_cast<bf16x8*>(&w);
;       asm volatile("" : "+v"(qr[d0])); }
;   }
;   { u32x4 w = {hi == 0 ? (cvtpk(negB, 0.f) & 0xffffu) : 0u, 0u, 0u, 0u}; qr[6] = *reinterpret_cast<bf16x8*>(&w); }
;   const int vb0 = (int)(uintptr_t)V_lds + v_rd_base(lane);
;   const int widu = __builtin_amdgcn_readfirstlane(wid);
;   const int kr0 = 8 * wid + (lane >> 4), kr1 = kr0 + 4, kp = lane & 15;
;   const int vkk = 8 * wid + ((lane & 31) >> 2), vk = (vkk & ~0xC) | ((vkk & 4) << 1) | ((vkk & 8) >> 1), vcc = 32 * (lane >> 5) + 8 * (lane & 3);
;   const bf16* kg0 = Kh + (long)kr0 * LDK + ((kp ^ (kr0 & 7)) * 8); const bf16* kg1 = Kh + (long)kr1 * LDK + ((kp ^ (kr1 & 7)) * 8); const bf16* vg = Vh + (long)vk * LDV + vcc;
;   LAS unsigned char* const lV = ldsl; LAS unsigned char* const lK = ldsl + 3 * SHM_V;
;     ...
;   f32x16 pA0, pA1, pB0, pB1; bf16x8 pa0, pa1, pa2, pa3; const int NT = seq / KVBLK;
;   DMA(0, 0); asm volatile("s_waitcnt vmcnt(0)" ::: "memory"); __syncthreads();
;   DMA(1, KVBLK);
	v_cndmask_b32_e64 v17, v45, -v45, s[6:7]
	v_cndmask_b32_e64 v39, v39, -v39, s[6:7]
	v_cndmask_b32_e64 v15, v37, -v37, s[6:7]
	v_cndmask_b32_e64 v37, v47, -v47, s[6:7]
	v_cndmask_b32_e64 v13, v11, -v11, s[6:7]
	v_pk_mul_f32 v[22:23], v[22:23], v[42:43]
	v_pk_mul_f32 v[18:19], v[24:25], v[18:19]
	v_pk_mul_f32 v[24:25], v[26:27], v[40:41]
	v_pk_mul_f32 v[16:17], v[28:29], v[16:17]
	v_pk_mul_f32 v[26:27], v[30:31], v[38:39]
	v_pk_mul_f32 v[14:15], v[32:33], v[14:15]
	v_pk_mul_f32 v[28:29], v[34:35], v[36:37]
	v_pk_mul_f32 v[12:13], v[20:21], v[12:13]
	v_add_f32_e32 v11, v22, v23
	v_add_f32_e32 v18, v18, v19
	v_add_f32_e32 v19, v24, v25
	v_add_f32_e32 v16, v16, v17
	v_add_f32_e32 v17, v26, v27
	v_add_f32_e32 v14, v14, v15
	v_add_f32_e32 v15, v28, v29
	v_add_f32_e32 v12, v12, v13
	v_cvt_pk_bf16_f32 v98, v12, v15
	v_cvt_pk_bf16_f32 v99, v14, v17
	v_cvt_pk_bf16_f32 v100, v16, v19
	v_cvt_pk_bf16_f32 v101, v18, v11
	v_mul_f32_e32 v34, v10, v0
	v_and_b32_e32 v6, 63, v44
	v_cvt_f32_ubyte0_e32 v6, v6
	v_mul_f32_e32 v11, 0x3a83126f, v6
	v_mul_f32_e32 v22, 0x3d0186e2, v6
	v_mul_f32_e32 v23, 0x3dcccccd, v6
	v_mul_f32_e32 v11, 0.15915494, v11
	v_mul_f32_e32 v7, 0x39a5cb5f, v6
	v_mul_f32_e32 v20, 0x3b4f3e37, v6
	v_mul_f32_e32 v21, 0x3c23d70a, v6
	v_mul_f32_e32 v24, 0x3ea1e89b, v6
	v_mul_f32_e32 v29, 0.15915494, v22
	v_mul_f32_e32 v31, 0.15915494, v23
	v_cos_f32_e32 v22, v11
	v_sin_f32_e32 v23, v11
	v_mul_f32_e32 v11, v10, v2
	v_mul_f32_e32 v25, 0.15915494, v6
	v_mul_f32_e32 v26, 0.15915494, v7
	v_mul_f32_e32 v27, 0.15915494, v20
	v_mul_f32_e32 v28, 0.15915494, v21
	v_mul_f32_e32 v33, 0.15915494, v24
	v_cos_f32_e32 v6, v25
	v_sin_f32_e32 v7, v25
	v_cos_f32_e32 v20, v26
	v_sin_f32_e32 v21, v26
	v_cos_f32_e32 v24, v27
	v_sin_f32_e32 v25, v27
	v_cos_f32_e32 v26, v28
	v_sin_f32_e32 v27, v28
	v_cos_f32_e32 v28, v29
	v_sin_f32_e32 v29, v29
	v_cos_f32_e32 v30, v31
	v_sin_f32_e32 v31, v31
	v_cos_f32_e32 v32, v33
	v_sin_f32_e32 v33, v33
	v_mul_f32_e32 v0, v8, v222
	v_mul_f32_e32 v2, v9, v223
	v_mul_f32_e32 v4, v4, v224
	v_mul_f32_e32 v8, v5, v225
	v_mul_f32_e32 v10, v11, v226
	v_mul_f32_e32 v12, v3, v227
	v_mul_f32_e32 v14, v34, v228
	v_mul_f32_e32 v16, v1, v229
	v_mov_b32_e32 v1, v0
	v_mov_b32_e32 v3, v0
	v_mov_b32_e32 v5, v2
	v_mov_b32_e32 v9, v2
	v_mov_b32_e32 v11, v4
	v_mov_b32_e32 v13, v4
	v_mov_b32_e32 v15, v8
	v_mov_b32_e32 v17, v8
	v_mov_b32_e32 v18, v10
	v_mov_b32_e32 v19, v10
	v_mov_b32_e32 v34, v12
	v_mov_b32_e32 v35, v12
	v_mov_b32_e32 v36, v14
	v_mov_b32_e32 v37, v14
	v_mov_b32_e32 v38, v16
	v_mov_b32_e32 v39, v16
	v_permlane32_swap_b32_e32 v1, v3
	v_permlane32_swap_b32_e32 v5, v9
	v_permlane32_swap_b32_e32 v11, v13
	v_permlane32_swap_b32_e32 v15, v17
	v_permlane32_swap_b32_e32 v18, v19
	v_permlane32_swap_b32_e32 v34, v35
	v_permlane32_swap_b32_e32 v36, v37
	v_permlane32_swap_b32_e32 v38, v39
	v_cndmask_b32_e64 v38, v38, v39, s[6:7]
	v_cndmask_b32_e64 v36, v36, v37, s[6:7]
	v_cndmask_b32_e64 v34, v34, v35, s[6:7]
	v_cndmask_b32_e64 v18, v18, v19, s[6:7]
	v_cndmask_b32_e64 v19, v15, v17, s[6:7]
	v_cndmask_b32_e64 v35, v11, v13, s[6:7]
	v_cndmask_b32_e64 v37, v5, v9, s[6:7]
	v_cndmask_b32_e64 v1, v1, v3, s[6:7]
	v_cndmask_b32_e64 v17, v38, -v38, s[6:7]
	v_cndmask_b32_e64 v15, v36, -v36, s[6:7]
	v_cndmask_b32_e64 v13, v34, -v34, s[6:7]
	v_cndmask_b32_e64 v11, v18, -v18, s[6:7]
	v_cndmask_b32_e64 v9, v19, -v19, s[6:7]
	v_cndmask_b32_e64 v5, v35, -v35, s[6:7]
	v_cndmask_b32_e64 v3, v37, -v37, s[6:7]
	v_cndmask_b32_e64 v1, v1, -v1, s[6:7]
	v_pk_mul_f32 v[16:17], v[20:21], v[16:17]
	v_pk_mul_f32 v[14:15], v[22:23], v[14:15]
	v_pk_mul_f32 v[12:13], v[24:25], v[12:13]
	v_pk_mul_f32 v[10:11], v[26:27], v[10:11]
	v_pk_mul_f32 v[8:9], v[28:29], v[8:9]
	v_pk_mul_f32 v[4:5], v[30:31], v[4:5]
	v_pk_mul_f32 v[2:3], v[32:33], v[2:3]
	v_pk_mul_f32 v[0:1], v[6:7], v[0:1]
	v_add_f32_e32 v6, v16, v17
	v_add_f32_e32 v7, v14, v15
	v_add_f32_e32 v12, v12, v13
	v_add_f32_e32 v10, v10, v11
	v_add_f32_e32 v8, v8, v9
	v_add_f32_e32 v4, v4, v5
	v_add_f32_e32 v2, v2, v3
	v_add_f32_e32 v0, v0, v1
	v_cvt_pk_bf16_f32 v102, v0, v2
	v_cvt_pk_bf16_f32 v103, v4, v8
	v_cvt_pk_bf16_f32 v104, v10, v12
	v_cvt_pk_bf16_f32 v105, v7, v6
	s_nop 0
	s_and_saveexec_b64 s[4:5], s[6:7]
	s_cbranch_execz .LBB0_1594
	v_mov_b32_e32 v0, s40
	v_cvt_pk_bf16_f32 v0, v0, v81
.LBB0_1594:
	s_or_b64 exec, exec, s[4:5]
	v_add_u32_e32 v134, 0xc000, v115
	v_mov_b64_e32 v[0:1], 0
	v_mov_b64_e32 v[2:3], 0
	v_mov_b64_e32 v[4:5], 0
	v_mov_b64_e32 v[6:7], 0
	v_mov_b64_e32 v[8:9], 0
	v_mov_b64_e32 v[10:11], 0
	v_mov_b64_e32 v[12:13], 0
	v_mov_b64_e32 v[14:15], 0
	v_mov_b64_e32 v[16:17], 0
	v_mov_b64_e32 v[18:19], 0
	v_mov_b64_e32 v[20:21], 0
	v_mov_b64_e32 v[22:23], 0
	v_mov_b64_e32 v[24:25], 0
	v_mov_b64_e32 v[26:27], 0
	v_mov_b64_e32 v[28:29], 0
	v_mov_b64_e32 v[30:31], 0
	v_mov_b32_e32 v133, 0
	v_mov_b32_e32 v135, 0
	s_cmp_ge_u32 s60, 0x2000
	s_cbranch_scc0 .Latt_noprio
	s_setprio 1
